# row sum-of-squares wave reductions (phase-0 conversion loops, final norm): xor-1,2,4,8 steps via DPP, xor-32 via permlane32 swap instead of ds_bpermute+wait
# speedup vs baseline: 1.0030x; 1.0030x over previous
.LBB0_17:
	global_load_dwordx4 v[12:15], v[2:3], off offset:-3072
	global_load_dwordx4 v[16:19], v[2:3], off offset:-2048
	global_load_dwordx4 v[20:23], v[2:3], off offset:-1024
	global_load_dwordx4 v[24:27], v[2:3], off
	global_load_dwordx4 v[28:31], v[0:1], off
	v_add_u32_e32 v4, s6, v4
	s_waitcnt vmcnt(4)
	v_mov_b32_e32 v34, v13
	s_waitcnt vmcnt(3)
	v_mov_b32_e32 v35, v17
	v_mov_b32_e32 v32, v12
	v_mov_b32_e32 v33, v16
	s_waitcnt vmcnt(2)
	v_mov_b32_e32 v42, v21
	s_waitcnt vmcnt(1)
	v_mov_b32_e32 v43, v25
	v_pk_mul_f32 v[34:35], v[34:35], v[34:35]
	v_mov_b32_e32 v36, v14
	v_mov_b32_e32 v37, v18
	v_mov_b32_e32 v40, v20
	v_mov_b32_e32 v41, v24
	v_pk_mul_f32 v[42:43], v[42:43], v[42:43]
	v_pk_fma_f32 v[32:33], v[32:33], v[32:33], v[34:35]
	v_mov_b32_e32 v38, v15
	v_mov_b32_e32 v39, v19
	v_mov_b32_e32 v44, v22
	v_mov_b32_e32 v45, v26
	v_pk_fma_f32 v[34:35], v[40:41], v[40:41], v[42:43]
	v_pk_fma_f32 v[32:33], v[36:37], v[36:37], v[32:33]
	v_mov_b32_e32 v46, v23
	v_mov_b32_e32 v47, v27
	v_pk_fma_f32 v[34:35], v[44:45], v[44:45], v[34:35]
	v_pk_fma_f32 v[32:33], v[38:39], v[38:39], v[32:33]
	v_pk_fma_f32 v[34:35], v[46:47], v[46:47], v[34:35]
	v_add_f32_e32 v11, v32, v33
	v_add_f32_e32 v11, v11, v34
	v_add_f32_e32 v11, v11, v35
	s_nop 1
	v_mov_b32_dpp v32, v11 quad_perm:[1,0,3,2] row_mask:0xf bank_mask:0xf
	s_waitcnt lgkmcnt(0)
	v_add_f32_e32 v11, v11, v32
	s_nop 1
	v_mov_b32_dpp v32, v11 quad_perm:[2,3,0,1] row_mask:0xf bank_mask:0xf
	s_waitcnt lgkmcnt(0)
	v_add_f32_e32 v11, v11, v32
	s_nop 1
	v_mov_b32_dpp v32, v11 row_half_mirror row_mask:0xf bank_mask:0xf
	s_waitcnt lgkmcnt(0)
	v_add_f32_e32 v11, v11, v32
	s_nop 1
	v_mov_b32_dpp v32, v11 row_mirror row_mask:0xf bank_mask:0xf
	s_waitcnt lgkmcnt(0)
	v_add_f32_e32 v11, v11, v32
	ds_bpermute_b32 v32, v9, v11
	s_waitcnt lgkmcnt(0)
	v_add_f32_e32 v11, v11, v32
	v_mov_b32_e32 v32, v11
	v_mov_b32_e32 v42, v11
	s_nop 1
	v_permlane32_swap_b32_e32 v32, v42
	s_waitcnt lgkmcnt(0)
	v_add_f32_e32 v11, v32, v42
	v_fmamk_f32 v11, v11, 0x3a800000, v187
	v_mul_f32_e32 v32, 0x4b800000, v11
	v_cmp_gt_f32_e32 vcc, s28, v11
	s_nop 1
	v_cndmask_b32_e32 v11, v11, v32, vcc
	v_rsq_f32_e32 v11, v11
	s_nop 0
	v_mul_f32_e32 v32, 0x45800000, v11
	v_cndmask_b32_e32 v32, v11, v32, vcc
	v_pk_mul_f32 v[12:13], v[12:13], v[32:33] op_sel_hi:[1,0]
	v_pk_mul_f32 v[14:15], v[14:15], v[32:33] op_sel_hi:[1,0]
	s_waitcnt vmcnt(0)
	v_pk_mul_f32 v[12:13], v[28:29], v[12:13]
	v_pk_mul_f32 v[14:15], v[30:31], v[14:15]
	global_store_dwordx4 v[2:3], v[12:15], off offset:-3072
	global_load_dwordx4 v[12:15], v[0:1], off offset:1024
	v_pk_mul_f32 v[18:19], v[18:19], v[32:33] op_sel_hi:[1,0]
	v_pk_mul_f32 v[16:17], v[16:17], v[32:33] op_sel_hi:[1,0]
	v_cmp_lt_i32_e32 vcc, s61, v4
	s_or_b64 s[10:11], vcc, s[10:11]
	s_waitcnt vmcnt(0)
	v_pk_mul_f32 v[12:13], v[12:13], v[16:17]
	v_pk_mul_f32 v[14:15], v[14:15], v[18:19]
	global_store_dwordx4 v[2:3], v[12:15], off offset:-2048
	global_load_dwordx4 v[12:15], v[0:1], off offset:2048
	v_pk_mul_f32 v[16:17], v[22:23], v[32:33] op_sel_hi:[1,0]
	v_pk_mul_f32 v[18:19], v[20:21], v[32:33] op_sel_hi:[1,0]
	s_waitcnt vmcnt(0)
	v_pk_mul_f32 v[14:15], v[14:15], v[16:17]
	v_pk_mul_f32 v[12:13], v[12:13], v[18:19]
	global_store_dwordx4 v[2:3], v[12:15], off offset:-1024
	global_load_dwordx4 v[12:15], v[0:1], off offset:3072
	v_pk_mul_f32 v[16:17], v[26:27], v[32:33] op_sel_hi:[1,0]
	v_pk_mul_f32 v[18:19], v[24:25], v[32:33] op_sel_hi:[1,0]
	s_waitcnt vmcnt(0)
	v_pk_mul_f32 v[14:15], v[14:15], v[16:17]
	v_pk_mul_f32 v[12:13], v[12:13], v[18:19]
	global_store_dwordx4 v[2:3], v[12:15], off
	v_lshl_add_u64 v[2:3], v[2:3], 0, s[8:9]
	s_andn2_b64 exec, exec, s[10:11]
	s_cbranch_execnz .LBB0_17

.LBB0_2006:
	global_load_dwordx4 v[18:21], v[8:9], off offset:-2048
	global_load_dwordx4 v[22:25], v[8:9], off offset:-1024
	global_load_dwordx4 v[26:29], v[8:9], off
	global_load_dwordx4 v[30:33], v[8:9], off offset:1024
	s_waitcnt vmcnt(0)
	v_cvt_pk_bf16_f32 v40, v18, v19
	v_cvt_pk_bf16_f32 v41, v20, v21
	global_store_dwordx2 v[6:7], v[40:41], off offset:-1024
	v_mul_f32_e32 v3, v19, v19
	s_waitcnt lgkmcnt(0)
	v_mul_f32_e32 v17, v21, v21
	v_fmac_f32_e32 v3, v18, v18
	v_fmac_f32_e32 v17, v20, v20
	v_add_f32_e32 v3, v3, v17
	v_cvt_pk_bf16_f32 v40, v22, v23
	v_cvt_pk_bf16_f32 v41, v24, v25
	global_store_dwordx2 v[6:7], v[40:41], off offset:-512
	v_mul_f32_e32 v17, v23, v23
	v_mul_f32_e32 v18, v25, v25
	v_fmac_f32_e32 v17, v22, v22
	v_fmac_f32_e32 v18, v24, v24
	v_add_f32_e32 v17, v17, v18
	v_add_f32_e32 v3, v3, v17
	v_cvt_pk_bf16_f32 v40, v26, v27
	v_cvt_pk_bf16_f32 v41, v28, v29
	global_store_dwordx2 v[6:7], v[40:41], off
	v_mul_f32_e32 v17, v27, v27
	v_mul_f32_e32 v18, v29, v29
	v_fmac_f32_e32 v17, v26, v26
	v_fmac_f32_e32 v18, v28, v28
	v_add_f32_e32 v17, v17, v18
	v_add_f32_e32 v3, v3, v17
	v_mul_f32_e32 v17, v31, v31
	v_mul_f32_e32 v18, v33, v33
	v_fmac_f32_e32 v17, v30, v30
	v_fmac_f32_e32 v18, v32, v32
	v_add_f32_e32 v17, v17, v18
	v_add_f32_e32 v3, v3, v17
	s_nop 1
	v_mov_b32_dpp v17, v3 quad_perm:[1,0,3,2] row_mask:0xf bank_mask:0xf
	v_cvt_pk_bf16_f32 v18, v30, v31
	v_cvt_pk_bf16_f32 v19, v32, v33
	global_store_dwordx2 v[6:7], v[18:19], off offset:512
	s_waitcnt lgkmcnt(0)
	v_add_f32_e32 v3, v3, v17
	s_nop 1
	v_mov_b32_dpp v17, v3 quad_perm:[2,3,0,1] row_mask:0xf bank_mask:0xf
	s_waitcnt lgkmcnt(0)
	v_add_f32_e32 v3, v3, v17
	s_nop 1
	v_mov_b32_dpp v17, v3 row_half_mirror row_mask:0xf bank_mask:0xf
	s_waitcnt lgkmcnt(0)
	v_add_f32_e32 v3, v3, v17
	s_nop 1
	v_mov_b32_dpp v17, v3 row_mirror row_mask:0xf bank_mask:0xf
	s_waitcnt lgkmcnt(0)
	v_add_f32_e32 v3, v3, v17
	ds_bpermute_b32 v17, v15, v3
	s_waitcnt lgkmcnt(0)
	v_add_f32_e32 v3, v3, v17
	v_mov_b32_e32 v17, v3
	v_mov_b32_e32 v42, v3
	s_nop 1
	v_permlane32_swap_b32_e32 v17, v42
	s_and_saveexec_b64 s[8:9], vcc
	s_cbranch_execz .LBB0_2005
	s_waitcnt lgkmcnt(0)
	v_add_f32_e32 v3, v17, v42
	v_cndmask_b32_e64 v3, 0, v3, s[6:7]
	global_store_dword v[4:5], v3, off
	s_branch .LBB0_2005

.LBB0_2011:
	global_load_dwordx4 v[16:19], v[8:9], off offset:-2048
	global_load_dwordx4 v[20:23], v[8:9], off offset:-1024
	global_load_dwordx4 v[24:27], v[8:9], off
	global_load_dwordx4 v[28:31], v[8:9], off offset:1024
	s_waitcnt vmcnt(0)
	v_cvt_pk_bf16_f32 v40, v16, v17
	v_cvt_pk_bf16_f32 v41, v18, v19
	global_store_dwordx2 v[6:7], v[40:41], off offset:-1024
	v_mul_f32_e32 v1, v17, v17
	s_waitcnt lgkmcnt(0)
	v_mul_f32_e32 v3, v19, v19
	v_fmac_f32_e32 v1, v16, v16
	v_fmac_f32_e32 v3, v18, v18
	v_add_f32_e32 v1, v1, v3
	v_cvt_pk_bf16_f32 v40, v20, v21
	v_cvt_pk_bf16_f32 v41, v22, v23
	global_store_dwordx2 v[6:7], v[40:41], off offset:-512
	v_mul_f32_e32 v3, v21, v21
	v_mul_f32_e32 v16, v23, v23
	v_fmac_f32_e32 v3, v20, v20
	v_fmac_f32_e32 v16, v22, v22
	v_add_f32_e32 v3, v3, v16
	v_add_f32_e32 v1, v1, v3
	v_cvt_pk_bf16_f32 v40, v24, v25
	v_cvt_pk_bf16_f32 v41, v26, v27
	global_store_dwordx2 v[6:7], v[40:41], off
	v_mul_f32_e32 v3, v25, v25
	v_mul_f32_e32 v16, v27, v27
	v_fmac_f32_e32 v3, v24, v24
	v_fmac_f32_e32 v16, v26, v26
	v_add_f32_e32 v3, v3, v16
	v_add_f32_e32 v1, v1, v3
	v_mul_f32_e32 v3, v29, v29
	v_mul_f32_e32 v16, v31, v31
	v_fmac_f32_e32 v3, v28, v28
	v_fmac_f32_e32 v16, v30, v30
	v_add_f32_e32 v3, v3, v16
	v_add_f32_e32 v1, v1, v3
	s_nop 1
	v_mov_b32_dpp v3, v1 quad_perm:[1,0,3,2] row_mask:0xf bank_mask:0xf
	v_cvt_pk_bf16_f32 v16, v28, v29
	v_cvt_pk_bf16_f32 v17, v30, v31
	global_store_dwordx2 v[6:7], v[16:17], off offset:512
	s_waitcnt lgkmcnt(0)
	v_add_f32_e32 v1, v1, v3
	s_nop 1
	v_mov_b32_dpp v3, v1 quad_perm:[2,3,0,1] row_mask:0xf bank_mask:0xf
	s_waitcnt lgkmcnt(0)
	v_add_f32_e32 v1, v1, v3
	s_nop 1
	v_mov_b32_dpp v3, v1 row_half_mirror row_mask:0xf bank_mask:0xf
	s_waitcnt lgkmcnt(0)
	v_add_f32_e32 v1, v1, v3
	s_nop 1
	v_mov_b32_dpp v3, v1 row_mirror row_mask:0xf bank_mask:0xf
	s_waitcnt lgkmcnt(0)
	v_add_f32_e32 v1, v1, v3
	ds_bpermute_b32 v3, v14, v1
	s_waitcnt lgkmcnt(0)
	v_add_f32_e32 v1, v1, v3
	v_mov_b32_e32 v3, v1
	v_mov_b32_e32 v42, v1
	s_nop 1
	v_permlane32_swap_b32_e32 v3, v42
	s_and_saveexec_b64 s[8:9], vcc
	s_cbranch_execz .LBB0_2010
	s_waitcnt lgkmcnt(0)
	v_add_f32_e32 v1, v3, v42
	v_cndmask_b32_e64 v1, 0, v1, s[6:7]
	global_store_dword v[4:5], v1, off
	s_branch .LBB0_2010
